# s5 gather loop 4 loads in flight
# speedup vs baseline: 1.0148x; 1.0015x over previous
.LBB0_1815:
	s_mov_b32 s21, 0x1fffff
	v_mov_b32_e32 v20, v0
	v_add_u32_e32 v40, s34, v20
	v_add_u32_e32 v60, s34, v40
	v_add_u32_e32 v80, s34, v60
	v_cmp_ge_i32_e64 s[40:41], s21, v20
	v_mov_b32_e32 v33, 0
	v_ashrrev_i32_e32 v24, 5, v20
	v_bfe_u32 v26, v20, 1, 4
	v_mov_b64_e32 v[22:23], s[24:25]
	v_lshrrev_b32_e32 v30, 4, v24
	v_mad_i64_i32 v[22:23], s[22:23], v24, s26, v[22:23]
	v_lshlrev_b32_e32 v32, 5, v26
	v_lshl_add_u64 v[22:23], v[22:23], 0, v[32:33]
	v_and_b32_e32 v32, 1, v20
	v_lshlrev_b32_e32 v32, 4, v32
	v_lshl_add_u64 v[22:23], v[22:23], 0, v[32:33]
	v_add_co_u32_e32 v22, vcc, 0x1000, v22
	v_ashrrev_i32_e32 v28, 9, v20
	s_nop 0
	v_addc_co_u32_e32 v23, vcc, 0, v23, vcc
	v_and_b32_e32 v28, 0xfffffe00, v28
	v_lshlrev_b32_e32 v26, 12, v26
	v_mov_b32_e32 v27, 0
	v_ashrrev_i32_e32 v29, 31, v28
	v_lshl_add_u64 v[26:27], v[26:27], 0, v[28:29]
	v_and_or_b32 v26, v30, s31, v26
	v_lshlrev_b64 v[26:27], 10, v[26:27]
	v_lshl_add_u64 v[26:27], s[38:39], 0, v[26:27]
	v_and_b32_e32 v28, 0x1e0, v20
	v_mov_b32_e32 v29, 0
	v_lshl_add_u64 v[26:27], v[26:27], 0, v[28:29]
	v_lshl_add_u64 v[26:27], v[26:27], 0, v[32:33]
	s_and_saveexec_b64 s[48:49], s[40:41]
	global_load_dwordx4 v[22:25], v[22:23], off offset:32
	s_mov_b64 exec, s[48:49]
	v_cmp_ge_i32_e64 s[42:43], s21, v40
	v_mov_b32_e32 v53, 0
	v_ashrrev_i32_e32 v44, 5, v40
	v_bfe_u32 v46, v40, 1, 4
	v_mov_b64_e32 v[42:43], s[24:25]
	v_lshrrev_b32_e32 v50, 4, v44
	v_mad_i64_i32 v[42:43], s[22:23], v44, s26, v[42:43]
	v_lshlrev_b32_e32 v52, 5, v46
	v_lshl_add_u64 v[42:43], v[42:43], 0, v[52:53]
	v_and_b32_e32 v52, 1, v40
	v_lshlrev_b32_e32 v52, 4, v52
	v_lshl_add_u64 v[42:43], v[42:43], 0, v[52:53]
	v_add_co_u32_e32 v42, vcc, 0x1000, v42
	v_ashrrev_i32_e32 v48, 9, v40
	s_nop 0
	v_addc_co_u32_e32 v43, vcc, 0, v43, vcc
	v_and_b32_e32 v48, 0xfffffe00, v48
	v_lshlrev_b32_e32 v46, 12, v46
	v_mov_b32_e32 v47, 0
	v_ashrrev_i32_e32 v49, 31, v48
	v_lshl_add_u64 v[46:47], v[46:47], 0, v[48:49]
	v_and_or_b32 v46, v50, s31, v46
	v_lshlrev_b64 v[46:47], 10, v[46:47]
	v_lshl_add_u64 v[46:47], s[38:39], 0, v[46:47]
	v_and_b32_e32 v48, 0x1e0, v40
	v_mov_b32_e32 v49, 0
	v_lshl_add_u64 v[46:47], v[46:47], 0, v[48:49]
	v_lshl_add_u64 v[46:47], v[46:47], 0, v[52:53]
	s_and_saveexec_b64 s[48:49], s[42:43]
	global_load_dwordx4 v[42:45], v[42:43], off offset:32
	s_mov_b64 exec, s[48:49]
	v_cmp_ge_i32_e64 s[44:45], s21, v60
	v_mov_b32_e32 v73, 0
	v_ashrrev_i32_e32 v64, 5, v60
	v_bfe_u32 v66, v60, 1, 4
	v_mov_b64_e32 v[62:63], s[24:25]
	v_lshrrev_b32_e32 v70, 4, v64
	v_mad_i64_i32 v[62:63], s[22:23], v64, s26, v[62:63]
	v_lshlrev_b32_e32 v72, 5, v66
	v_lshl_add_u64 v[62:63], v[62:63], 0, v[72:73]
	v_and_b32_e32 v72, 1, v60
	v_lshlrev_b32_e32 v72, 4, v72
	v_lshl_add_u64 v[62:63], v[62:63], 0, v[72:73]
	v_add_co_u32_e32 v62, vcc, 0x1000, v62
	v_ashrrev_i32_e32 v68, 9, v60
	s_nop 0
	v_addc_co_u32_e32 v63, vcc, 0, v63, vcc
	v_and_b32_e32 v68, 0xfffffe00, v68
	v_lshlrev_b32_e32 v66, 12, v66
	v_mov_b32_e32 v67, 0
	v_ashrrev_i32_e32 v69, 31, v68
	v_lshl_add_u64 v[66:67], v[66:67], 0, v[68:69]
	v_and_or_b32 v66, v70, s31, v66
	v_lshlrev_b64 v[66:67], 10, v[66:67]
	v_lshl_add_u64 v[66:67], s[38:39], 0, v[66:67]
	v_and_b32_e32 v68, 0x1e0, v60
	v_mov_b32_e32 v69, 0
	v_lshl_add_u64 v[66:67], v[66:67], 0, v[68:69]
	v_lshl_add_u64 v[66:67], v[66:67], 0, v[72:73]
	s_and_saveexec_b64 s[48:49], s[44:45]
	global_load_dwordx4 v[62:65], v[62:63], off offset:32
	s_mov_b64 exec, s[48:49]
	v_cmp_ge_i32_e64 s[46:47], s21, v80
	v_mov_b32_e32 v93, 0
	v_ashrrev_i32_e32 v84, 5, v80
	v_bfe_u32 v86, v80, 1, 4
	v_mov_b64_e32 v[82:83], s[24:25]
	v_lshrrev_b32_e32 v90, 4, v84
	v_mad_i64_i32 v[82:83], s[22:23], v84, s26, v[82:83]
	v_lshlrev_b32_e32 v92, 5, v86
	v_lshl_add_u64 v[82:83], v[82:83], 0, v[92:93]
	v_and_b32_e32 v92, 1, v80
	v_lshlrev_b32_e32 v92, 4, v92
	v_lshl_add_u64 v[82:83], v[82:83], 0, v[92:93]
	v_add_co_u32_e32 v82, vcc, 0x1000, v82
	v_ashrrev_i32_e32 v88, 9, v80
	s_nop 0
	v_addc_co_u32_e32 v83, vcc, 0, v83, vcc
	v_and_b32_e32 v88, 0xfffffe00, v88
	v_lshlrev_b32_e32 v86, 12, v86
	v_mov_b32_e32 v87, 0
	v_ashrrev_i32_e32 v89, 31, v88
	v_lshl_add_u64 v[86:87], v[86:87], 0, v[88:89]
	v_and_or_b32 v86, v90, s31, v86
	v_lshlrev_b64 v[86:87], 10, v[86:87]
	v_lshl_add_u64 v[86:87], s[38:39], 0, v[86:87]
	v_and_b32_e32 v88, 0x1e0, v80
	v_mov_b32_e32 v89, 0
	v_lshl_add_u64 v[86:87], v[86:87], 0, v[88:89]
	v_lshl_add_u64 v[86:87], v[86:87], 0, v[92:93]
	s_and_saveexec_b64 s[48:49], s[46:47]
	global_load_dwordx4 v[82:85], v[82:83], off offset:32
	s_mov_b64 exec, s[48:49]
	s_waitcnt vmcnt(0)
	s_and_saveexec_b64 s[48:49], s[40:41]
	global_store_dwordx4 v[26:27], v[22:25], off
	s_mov_b64 exec, s[48:49]
	s_and_saveexec_b64 s[48:49], s[42:43]
	global_store_dwordx4 v[46:47], v[42:45], off
	s_mov_b64 exec, s[48:49]
	s_and_saveexec_b64 s[48:49], s[44:45]
	global_store_dwordx4 v[66:67], v[62:65], off
	s_mov_b64 exec, s[48:49]
	s_and_saveexec_b64 s[48:49], s[46:47]
	global_store_dwordx4 v[86:87], v[82:85], off
	s_mov_b64 exec, s[48:49]
	v_add_u32_e32 v0, s34, v80
	v_cmp_ge_i32_e32 vcc, s21, v0
	s_and_b64 exec, exec, vcc
	s_cbranch_execnz .LBB0_1815
